# attention step head: K-fragment LDS reads issued before the V-fragment transpose reads, first wait relaxed to lgkmcnt(4) (on top of v57)
# baseline (speedup 1.0000x reference)
; #define ATT_WAIT_BAR() asm volatile("s_waitcnt vmcnt(0) lgkmcnt(0)\n\ts_barrier" ::: "memory")
; #define ATT_SB() __builtin_amdgcn_sched_barrier(0)
; #define A16_VLD(v, g) do { const LAS unsigned char* a_ = vbp[(g) & 3] + vso + ((g) >> 4) * 16384 + (((g) & 15) >> 2) * 1024; v[0] = vtr(a_); v[1] = vtr(a_ + 8192); } while (0)
; #define A16_GAP(i) do { A16_EL(i) = __builtin_amdgcn_exp2f(A16_EL(i)); \
;                 if ((i) > 0) { if ((((i) - 1) >> 2) & 1) s1 += A16_EL((i) - 1); else s0 += A16_EL((i) - 1); } asm volatile("" : "+v"(s0), "+v"(s1)); } while (0)
; __device__ __forceinline__ void attn_core16(f32x4 (&O)[16][2], float (&lq)[2], const bf16_t* Qw, int q_pitch, const bf16_t* Kh, const bf16_t* Vh, int kv_pitch,
;                                             int NT, int nt_act, int kch0, float negb, LAS unsigned char* ring, int wid) {
;     ...
;         ATT_WAIT_BAR();
;         if (t < nt_act) {
;             const bool more = (t + 1 < nt_act);
;             const int vso = (t & 1) * SLOTB;
;             s16x4 vv[3][2];
;     ...
;             A16_VLD(vv[0], 0);
;             ATT_SB();
;             A16_QK(t + 1, 1, t);
;             ATT_SB();
;             A16_VLD(vv[1], 1);
;             float s0 = 0.f, s1 = 0.f;
;     ...
; #pragma unroll
;             for (int g = 0; g < 32; ++g) {
;                 if (g + 2 < 32) A16_VLD(vv[(g + 2) % 3], g + 2);
;                 ATT_SB();
;                 O[g & 15][0] = __builtin_amdgcn_mfma_f32_16x16x32_bf16(A16_VF(vv[g % 3]), __builtin_bit_cast(bf16x8, pw[g >> 4][0]), O[g & 15][0], 0, 0, 0);
;                 O[g & 15][1] = __builtin_amdgcn_mfma_f32_16x16x32_bf16(A16_VF(vv[g % 3]), __builtin_bit_cast(bf16x8, pw[g >> 4][1]), O[g & 15][1], 0, 0, 0);
;                 A16_GAP(g);
.LBB0_685:
	s_waitcnt vmcnt(0) lgkmcnt(0)
	s_barrier
	s_add_i32 s20, s0, 1
	s_cmp_ge_u32 s0, s73
	s_cbranch_scc1 .LBB0_687
	s_and_b32 s80, s72, 0x10000
	v_add_u32_e32 v2, s80, v214
	ds_read_b128 v[188:191], v2
	ds_read_b128 v[192:195], v2 offset:8192
	s_add_i32 s48, s72, 0xffff0000
	s_and_b32 s50, s48, 0x10000
	v_add_u32_e32 v0, s50, v216
	ds_read_b64_tr_b16 v[220:221], v0 offset:32768
	ds_read_b64_tr_b16 v[222:223], v0 offset:40960
	s_add_i32 s0, s0, 2
	s_min_u32 vcc_lo, s0, s21
	s_min_u32 s0, s20, s21
	s_lshl_b64 s[70:71], s[0:1], 18
	s_add_u32 s70, s38, s70
	s_mov_b32 vcc_hi, s1
	ds_read_b128 v[200:203], v2 offset:16384
	s_addc_u32 s71, s39, s71
	s_add_i32 s0, s12, s80
	s_lshl_b64 vcc, vcc, 18
	s_add_u32 s54, s18, vcc_lo
	s_addc_u32 s55, s19, vcc_hi
	s_add_i32 vcc_lo, s13, s50
	s_waitcnt lgkmcnt(4)
	v_mfma_f32_16x16x32_bf16 v[196:199], v[188:191], v[136:139], v[168:171]
	s_mov_b32 s48, m0
	s_mov_b32 m0, vcc_lo
	s_nop 0
	global_load_lds_dwordx4 v212, s[54:55]
	s_mov_b32 m0, s48
	v_mfma_f32_16x16x32_bf16 v[188:191], v[188:191], v[152:155], v[168:171]
	ds_read_b128 v[204:207], v2 offset:24576
	s_add_u32 s48, s54, 0x80
	s_waitcnt lgkmcnt(2)
	v_mfma_f32_16x16x32_bf16 v[224:227], v[192:195], v[136:139], v[168:171]
	s_addc_u32 s49, s55, 0
	s_add_i32 vcc_hi, vcc_lo, 0x400
	s_mov_b32 s9, m0
	s_mov_b32 m0, vcc_hi
	s_nop 0
	global_load_lds_dwordx4 v212, s[48:49]
	s_mov_b32 m0, s9
	v_mfma_f32_16x16x32_bf16 v[192:195], v[192:195], v[152:155], v[168:171]
	v_add_u32_e32 v3, s80, v215
	ds_read_b128 v[230:233], v3
	s_add_u32 s48, s54, 0x100
	s_waitcnt lgkmcnt(2)
	v_mfma_f32_16x16x32_bf16 v[234:237], v[200:203], v[136:139], v[168:171]
	s_addc_u32 s49, s55, 0
	s_add_i32 s9, vcc_lo, 0x800
	s_mov_b32 s80, m0
	s_mov_b32 m0, s9
	s_nop 0
	global_load_lds_dwordx4 v212, s[48:49]
	s_mov_b32 m0, s80
	v_mfma_f32_16x16x32_bf16 v[200:203], v[200:203], v[152:155], v[168:171]
	ds_read_b128 v[238:241], v3 offset:8192
	s_add_u32 s48, s54, 0x180
	s_waitcnt lgkmcnt(2)
	v_mfma_f32_16x16x32_bf16 v[242:245], v[204:207], v[136:139], v[168:171]
	s_addc_u32 s49, s55, 0
	s_add_i32 s9, vcc_lo, 0xc00
	s_mov_b32 s54, m0
	s_mov_b32 m0, s9
	s_nop 0
	global_load_lds_dwordx4 v212, s[48:49]
	s_mov_b32 m0, s54
	v_mfma_f32_16x16x32_bf16 v[204:207], v[204:207], v[152:155], v[168:171]
	ds_read_b128 v[246:249], v3 offset:16384
	s_waitcnt lgkmcnt(2)
	v_mfma_f32_16x16x32_bf16 v[196:199], v[230:233], v[140:143], v[196:199]
	s_mov_b32 s9, m0
	s_mov_b32 m0, s0
	s_nop 0
	global_load_lds_dwordx4 v213, s[70:71]
	s_mov_b32 m0, s9
	v_mfma_f32_16x16x32_bf16 v[188:191], v[230:233], v[156:159], v[188:191]
	ds_read_b128 v[230:233], v3 offset:24576
	s_add_u32 s48, s70, 0x80
	s_waitcnt lgkmcnt(2)
	v_mfma_f32_16x16x32_bf16 v[192:195], v[238:241], v[156:159], v[192:195]
	s_addc_u32 s49, s71, 0
	s_add_i32 s9, s0, 0x400
	s_mov_b32 s54, m0
	s_mov_b32 m0, s9
	s_nop 0
	global_load_lds_dwordx4 v213, s[48:49]
	s_mov_b32 m0, s54
	v_mfma_f32_16x16x32_bf16 v[224:227], v[238:241], v[140:143], v[224:227]
	ds_read_b128 v[238:241], v2 offset:1024
	s_add_u32 s48, s70, 0x100
	s_waitcnt lgkmcnt(2)
	v_mfma_f32_16x16x32_bf16 v[234:237], v[246:249], v[140:143], v[234:237]
	s_addc_u32 s49, s71, 0
	s_add_i32 s9, s0, 0x800
	s_mov_b32 s54, m0
	s_mov_b32 m0, s9
	s_nop 0
	global_load_lds_dwordx4 v213, s[48:49]
	s_mov_b32 m0, s54
	v_mfma_f32_16x16x32_bf16 v[200:203], v[246:249], v[156:159], v[200:203]
	ds_read_b128 v[246:249], v2 offset:9216
	s_add_u32 s48, s70, 0x180
	s_waitcnt lgkmcnt(2)
	v_mfma_f32_16x16x32_bf16 v[204:207], v[230:233], v[156:159], v[204:207]
	s_addc_u32 s49, s71, 0
	s_addk_i32 s0, 0xc00
	s_mov_b32 s9, m0
	s_mov_b32 m0, s0
	s_nop 0
	global_load_lds_dwordx4 v213, s[48:49]
	s_mov_b32 m0, s9
	v_mfma_f32_16x16x32_bf16 v[242:245], v[230:233], v[140:143], v[242:245]
	ds_read_b128 v[230:233], v2 offset:17408
	s_waitcnt lgkmcnt(2)
	v_mfma_f32_16x16x32_bf16 v[196:199], v[238:241], v[144:147], v[196:199]
	v_mfma_f32_16x16x32_bf16 v[188:191], v[238:241], v[160:163], v[188:191]
	ds_read_b128 v[238:241], v2 offset:25600
	s_waitcnt lgkmcnt(2)
	v_mfma_f32_16x16x32_bf16 v[192:195], v[246:249], v[160:163], v[192:195]
	v_mfma_f32_16x16x32_bf16 v[224:227], v[246:249], v[144:147], v[224:227]
	ds_read_b128 v[246:249], v3 offset:1024
	s_waitcnt lgkmcnt(2)
	v_mfma_f32_16x16x32_bf16 v[234:237], v[230:233], v[144:147], v[234:237]
	v_mfma_f32_16x16x32_bf16 v[230:233], v[230:233], v[160:163], v[200:203]
	s_nop 2
	ds_read_b128 v[200:203], v3 offset:9216
	s_waitcnt lgkmcnt(2)
	v_mfma_f32_16x16x32_bf16 v[242:245], v[238:241], v[144:147], v[242:245]
	v_mfma_f32_16x16x32_bf16 v[238:241], v[238:241], v[160:163], v[204:207]
	s_waitcnt lgkmcnt(1)
	v_mfma_f32_16x16x32_bf16 v[250:253], v[246:249], v[148:151], v[196:199]
	s_nop 2
	ds_read_b128 v[196:199], v3 offset:17408
	v_mfma_f32_16x16x32_bf16 v[246:249], v[246:249], v[164:167], v[188:191]
	s_nop 2
	ds_read_b128 v[188:191], v3 offset:25600
	s_waitcnt lgkmcnt(2)
	v_mfma_f32_16x16x32_bf16 v[224:227], v[200:203], v[148:151], v[224:227]
	v_mfma_f32_16x16x32_bf16 v[204:207], v[200:203], v[164:167], v[192:195]
	s_waitcnt lgkmcnt(1)
	v_mfma_f32_16x16x32_bf16 v[200:203], v[196:199], v[148:151], v[234:237]
	v_mfma_f32_16x16x32_bf16 v[196:199], v[196:199], v[164:167], v[230:233]
	s_waitcnt lgkmcnt(0)
	v_mfma_f32_16x16x32_bf16 v[192:195], v[188:191], v[148:151], v[242:245]
	v_mfma_f32_16x16x32_bf16 v[188:191], v[188:191], v[164:167], v[238:241]
	v_add_u32_e32 v229, s50, v217
	s_nop 1
	v_add_u32_e32 v238, s50, v218
	ds_read_b64_tr_b16 v[230:231], v229 offset:32768
	ds_read_b64_tr_b16 v[232:233], v229 offset:40960
	ds_read_b64_tr_b16 v[234:235], v238 offset:32768
	ds_read_b64_tr_b16 v[236:237], v238 offset:40960
	v_mfma_f32_16x16x32_bf16 v[68:71], v[220:223], v[184:187], v[68:71]
	v_mov_b32_e32 v239, 0
	v_mov_b32_e32 v240, 0
	v_exp_f32_e32 v2, v250
	v_mfma_f32_16x16x32_bf16 v[132:135], v[220:223], v[180:183], v[132:135]
	v_add_u32_e32 v241, s50, v219
	ds_read_b64_tr_b16 v[220:221], v241 offset:32768
	ds_read_b64_tr_b16 v[222:223], v241 offset:40960
	s_waitcnt lgkmcnt(4)
; #define ATT_SB() __builtin_amdgcn_sched_barrier(0)
; #define A16_VLD(v, g) do { const LAS unsigned char* a_ = vbp[(g) & 3] + vso + ((g) >> 4) * 16384 + (((g) & 15) >> 2) * 1024; v[0] = vtr(a_); v[1] = vtr(a_ + 8192); } while (0)
; #define A16_GAP(i) do { A16_EL(i) = __builtin_amdgcn_exp2f(A16_EL(i)); \
;                 if ((i) > 0) { if ((((i) - 1) >> 2) & 1) s1 += A16_EL((i) - 1); else s0 += A16_EL((i) - 1); } asm volatile("" : "+v"(s0), "+v"(s1)); } while (0)
; __device__ __forceinline__ void attn_core16(f32x4 (&O)[16][2], float (&lq)[2], const bf16_t* Qw, int q_pitch, const bf16_t* Kh, const bf16_t* Vh, int kv_pitch,
;                                             int NT, int nt_act, int kch0, float negb, LAS unsigned char* ring, int wid) {
;     ...
;             A16_VLD(vv[0], 0);
;             ATT_SB();
;             A16_QK(t + 1, 1, t);
;             ATT_SB();
;             A16_VLD(vv[1], 1);
;             float s0 = 0.f, s1 = 0.f;
;     ...
; #pragma unroll
;             for (int g = 0; g < 32; ++g) {
;                 if (g + 2 < 32) A16_VLD(vv[(g + 2) % 3], g + 2);
;                 ATT_SB();
;                 O[g & 15][0] = __builtin_amdgcn_mfma_f32_16x16x32_bf16(A16_VF(vv[g % 3]), __builtin_bit_cast(bf16x8, pw[g >> 4][0]), O[g & 15][0], 0, 0, 0);
;                 O[g & 15][1] = __builtin_amdgcn_mfma_f32_16x16x32_bf16(A16_VF(vv[g % 3]), __builtin_bit_cast(bf16x8, pw[g >> 4][1]), O[g & 15][1], 0, 0, 0);
;                 A16_GAP(g);
;                 ATT_SB();
;             }
	v_mfma_f32_16x16x32_bf16 v[128:131], v[230:233], v[180:183], v[128:131]
	v_add_f32_e32 v239, v2, v239
	v_exp_f32_e32 v3, v251
	v_mfma_f32_16x16x32_bf16 v[64:67], v[230:233], v[184:187], v[64:67]
	ds_read_b64_tr_b16 v[230:231], v0 offset:33792
	ds_read_b64_tr_b16 v[232:233], v0 offset:41984
	s_waitcnt lgkmcnt(4)
	v_mfma_f32_16x16x32_bf16 v[60:63], v[234:237], v[184:187], v[60:63]
	v_add_f32_e32 v239, v3, v239
	v_exp_f32_e32 v242, v252
	v_mfma_f32_16x16x32_bf16 v[124:127], v[234:237], v[180:183], v[124:127]
	ds_read_b64_tr_b16 v[234:235], v229 offset:33792
	ds_read_b64_tr_b16 v[236:237], v229 offset:41984
	s_waitcnt lgkmcnt(4)
	v_mfma_f32_16x16x32_bf16 v[120:123], v[220:223], v[180:183], v[120:123]
	v_add_f32_e32 v239, v242, v239
	v_exp_f32_e32 v243, v253
	v_mfma_f32_16x16x32_bf16 v[56:59], v[220:223], v[184:187], v[56:59]
	ds_read_b64_tr_b16 v[220:221], v238 offset:33792
	ds_read_b64_tr_b16 v[222:223], v238 offset:41984
	s_waitcnt lgkmcnt(4)
	v_mfma_f32_16x16x32_bf16 v[52:55], v[230:233], v[184:187], v[52:55]
	v_add_f32_e32 v239, v243, v239
	v_exp_f32_e32 v244, v246
	v_mfma_f32_16x16x32_bf16 v[116:119], v[230:233], v[180:183], v[116:119]
	ds_read_b64_tr_b16 v[230:231], v241 offset:33792
	ds_read_b64_tr_b16 v[232:233], v241 offset:41984
	s_waitcnt lgkmcnt(4)
	v_mfma_f32_16x16x32_bf16 v[112:115], v[234:237], v[180:183], v[112:115]
	v_add_f32_e32 v240, v244, v240
	v_exp_f32_e32 v245, v247
	v_mfma_f32_16x16x32_bf16 v[48:51], v[234:237], v[184:187], v[48:51]
	ds_read_b64_tr_b16 v[234:235], v0 offset:34816
	ds_read_b64_tr_b16 v[236:237], v0 offset:43008
	s_waitcnt lgkmcnt(4)
	v_mfma_f32_16x16x32_bf16 v[44:47], v[220:223], v[184:187], v[44:47]
	v_add_f32_e32 v240, v245, v240
	v_exp_f32_e32 v246, v248
	v_mfma_f32_16x16x32_bf16 v[108:111], v[220:223], v[180:183], v[108:111]
	ds_read_b64_tr_b16 v[220:221], v229 offset:34816
	ds_read_b64_tr_b16 v[222:223], v229 offset:43008
	s_waitcnt lgkmcnt(4)
	v_mfma_f32_16x16x32_bf16 v[104:107], v[230:233], v[180:183], v[104:107]
	v_add_f32_e32 v240, v246, v240
	v_exp_f32_e32 v247, v249
	v_mfma_f32_16x16x32_bf16 v[40:43], v[230:233], v[184:187], v[40:43]
	ds_read_b64_tr_b16 v[230:231], v238 offset:34816
	ds_read_b64_tr_b16 v[232:233], v238 offset:43008
	s_waitcnt lgkmcnt(4)
	v_mfma_f32_16x16x32_bf16 v[36:39], v[234:237], v[184:187], v[36:39]
	v_add_f32_e32 v240, v247, v240
	v_exp_f32_e32 v248, v224
	v_mfma_f32_16x16x32_bf16 v[100:103], v[234:237], v[180:183], v[100:103]
	ds_read_b64_tr_b16 v[234:235], v241 offset:34816
	ds_read_b64_tr_b16 v[236:237], v241 offset:43008
	s_waitcnt lgkmcnt(4)
	v_mfma_f32_16x16x32_bf16 v[96:99], v[220:223], v[180:183], v[96:99]
	v_add_f32_e32 v224, v248, v239
	v_exp_f32_e32 v249, v225
	v_mfma_f32_16x16x32_bf16 v[32:35], v[220:223], v[184:187], v[32:35]
	ds_read_b64_tr_b16 v[220:221], v0 offset:35840
	ds_read_b64_tr_b16 v[222:223], v0 offset:44032
	s_waitcnt lgkmcnt(4)
	v_mfma_f32_16x16x32_bf16 v[28:31], v[230:233], v[184:187], v[28:31]
	v_add_f32_e32 v224, v249, v224
	v_exp_f32_e32 v239, v226
	v_mfma_f32_16x16x32_bf16 v[92:95], v[230:233], v[180:183], v[92:95]
	ds_read_b64_tr_b16 v[230:231], v229 offset:35840
	ds_read_b64_tr_b16 v[232:233], v229 offset:44032
	s_waitcnt lgkmcnt(4)
	v_mfma_f32_16x16x32_bf16 v[88:91], v[234:237], v[180:183], v[88:91]
	v_add_f32_e32 v251, v239, v224
	v_exp_f32_e32 v250, v227
	v_mfma_f32_16x16x32_bf16 v[24:27], v[234:237], v[184:187], v[24:27]
	ds_read_b64_tr_b16 v[224:225], v238 offset:35840
	ds_read_b64_tr_b16 v[226:227], v238 offset:44032
	s_waitcnt lgkmcnt(4)
	v_mfma_f32_16x16x32_bf16 v[20:23], v[220:223], v[184:187], v[20:23]
	v_exp_f32_e32 v234, v204
	v_add_f32_e32 v204, v250, v251
	v_mfma_f32_16x16x32_bf16 v[84:87], v[220:223], v[180:183], v[84:87]
	ds_read_b64_tr_b16 v[220:221], v241 offset:35840
	ds_read_b64_tr_b16 v[222:223], v241 offset:44032
	s_waitcnt lgkmcnt(4)
	v_mfma_f32_16x16x32_bf16 v[80:83], v[230:233], v[180:183], v[80:83]
	v_exp_f32_e32 v235, v205
	v_add_f32_e32 v205, v234, v240
	v_mfma_f32_16x16x32_bf16 v[16:19], v[230:233], v[184:187], v[16:19]
	ds_read_b64_tr_b16 v[230:231], v0 offset:49152
	ds_read_b64_tr_b16 v[232:233], v0 offset:57344
	s_waitcnt lgkmcnt(4)
	v_mfma_f32_16x16x32_bf16 v[12:15], v[224:227], v[184:187], v[12:15]
	v_add_f32_e32 v205, v235, v205
	v_exp_f32_e32 v236, v206
	v_mfma_f32_16x16x32_bf16 v[76:79], v[224:227], v[180:183], v[76:79]
	ds_read_b64_tr_b16 v[224:225], v229 offset:49152
	ds_read_b64_tr_b16 v[226:227], v229 offset:57344
	s_waitcnt lgkmcnt(4)
	v_mfma_f32_16x16x32_bf16 v[8:11], v[220:223], v[184:187], v[8:11]
	v_add_f32_e32 v184, v236, v205
	v_exp_f32_e32 v237, v207
	v_mfma_f32_16x16x32_bf16 v[72:75], v[220:223], v[180:183], v[72:75]
	ds_read_b64_tr_b16 v[180:181], v238 offset:49152
	ds_read_b64_tr_b16 v[182:183], v238 offset:57344
	s_waitcnt lgkmcnt(4)
	v_mfma_f32_16x16x32_bf16 v[68:71], v[230:233], v[176:179], v[68:71]
	v_add_f32_e32 v221, v237, v184
	v_exp_f32_e32 v220, v200
	v_mfma_f32_16x16x32_bf16 v[132:135], v[230:233], v[172:175], v[132:135]
	ds_read_b64_tr_b16 v[184:185], v241 offset:49152
	ds_read_b64_tr_b16 v[186:187], v241 offset:57344
	s_waitcnt lgkmcnt(4)
; #define ATT_SB() __builtin_amdgcn_sched_barrier(0)
; #define A16_PACK() do { _Pragma("unroll") for (int p_ = 0; p_ < 2; ++p_) _Pragma("unroll") for (int h_ = 0; h_ < 2; ++h_) \
;         pw[p_][h_] = (u32x4){pk2(S[2 * p_][h_][0], S[2 * p_][h_][1]), pk2(S[2 * p_][h_][2], S[2 * p_][h_][3]), pk2(S[2 * p_ + 1][h_][0], S[2 * p_ + 1][h_][1]), pk2(S[2 * p_ + 1][h_][2], S[2 * p_ + 1][h_][3])}; } while (0)
; #define A16_VLD(v, g) do { const LAS unsigned char* a_ = vbp[(g) & 3] + vso + ((g) >> 4) * 16384 + (((g) & 15) >> 2) * 1024; v[0] = vtr(a_); v[1] = vtr(a_ + 8192); } while (0)
; #define A16_GAP(i) do { A16_EL(i) = __builtin_amdgcn_exp2f(A16_EL(i)); \
;                 if ((i) > 0) { if ((((i) - 1) >> 2) & 1) s1 += A16_EL((i) - 1); else s0 += A16_EL((i) - 1); } asm volatile("" : "+v"(s0), "+v"(s1)); } while (0)
; __device__ __forceinline__ void attn_core16(f32x4 (&O)[16][2], float (&lq)[2], const bf16_t* Qw, int q_pitch, const bf16_t* Kh, const bf16_t* Vh, int kv_pitch,
;                                             int NT, int nt_act, int kch0, float negb, LAS unsigned char* ring, int wid) {
;     ...
; #pragma unroll
;             for (int g = 0; g < 32; ++g) {
;                 if (g + 2 < 32) A16_VLD(vv[(g + 2) % 3], g + 2);
;                 ATT_SB();
;                 O[g & 15][0] = __builtin_amdgcn_mfma_f32_16x16x32_bf16(A16_VF(vv[g % 3]), __builtin_bit_cast(bf16x8, pw[g >> 4][0]), O[g & 15][0], 0, 0, 0);
;                 O[g & 15][1] = __builtin_amdgcn_mfma_f32_16x16x32_bf16(A16_VF(vv[g % 3]), __builtin_bit_cast(bf16x8, pw[g >> 4][1]), O[g & 15][1], 0, 0, 0);
;                 A16_GAP(g);
;                 ATT_SB();
;             }
;     ...
;             l0 += more ? s0 : 0.f; l1 += more ? (s1 + A16_EL(31)) : 0.f;
;             A16_PACK();
	v_mfma_f32_16x16x32_bf16 v[128:131], v[224:227], v[172:175], v[128:131]
	v_add_f32_e32 v200, v220, v204
	v_exp_f32_e32 v222, v201
	v_mfma_f32_16x16x32_bf16 v[64:67], v[224:227], v[176:179], v[64:67]
	ds_read_b64_tr_b16 v[204:205], v0 offset:50176
	ds_read_b64_tr_b16 v[206:207], v0 offset:58368
	s_waitcnt lgkmcnt(4)
	v_mfma_f32_16x16x32_bf16 v[60:63], v[180:183], v[176:179], v[60:63]
	v_add_f32_e32 v200, v222, v200
	v_exp_f32_e32 v223, v202
	v_mfma_f32_16x16x32_bf16 v[124:127], v[180:183], v[172:175], v[124:127]
	ds_read_b64_tr_b16 v[180:181], v229 offset:50176
	ds_read_b64_tr_b16 v[182:183], v229 offset:58368
	s_waitcnt lgkmcnt(4)
	v_mfma_f32_16x16x32_bf16 v[120:123], v[184:187], v[172:175], v[120:123]
	v_add_f32_e32 v200, v223, v200
	v_exp_f32_e32 v224, v203
	v_mfma_f32_16x16x32_bf16 v[56:59], v[184:187], v[176:179], v[56:59]
	ds_read_b64_tr_b16 v[184:185], v238 offset:50176
	ds_read_b64_tr_b16 v[186:187], v238 offset:58368
	s_waitcnt lgkmcnt(4)
	v_mfma_f32_16x16x32_bf16 v[52:55], v[204:207], v[176:179], v[52:55]
	v_add_f32_e32 v226, v224, v200
	v_exp_f32_e32 v225, v196
	v_mfma_f32_16x16x32_bf16 v[116:119], v[204:207], v[172:175], v[116:119]
	ds_read_b64_tr_b16 v[200:201], v241 offset:50176
	ds_read_b64_tr_b16 v[202:203], v241 offset:58368
	s_waitcnt lgkmcnt(4)
	v_mfma_f32_16x16x32_bf16 v[112:115], v[180:183], v[172:175], v[112:115]
	v_add_f32_e32 v196, v225, v221
	v_exp_f32_e32 v204, v197
	v_mfma_f32_16x16x32_bf16 v[48:51], v[180:183], v[176:179], v[48:51]
	ds_read_b64_tr_b16 v[180:181], v0 offset:51200
	ds_read_b64_tr_b16 v[182:183], v0 offset:59392
	s_waitcnt lgkmcnt(4)
	v_mfma_f32_16x16x32_bf16 v[44:47], v[184:187], v[176:179], v[44:47]
	v_add_f32_e32 v196, v204, v196
	v_exp_f32_e32 v205, v198
	v_mfma_f32_16x16x32_bf16 v[108:111], v[184:187], v[172:175], v[108:111]
	ds_read_b64_tr_b16 v[184:185], v229 offset:51200
	ds_read_b64_tr_b16 v[186:187], v229 offset:59392
	s_waitcnt lgkmcnt(4)
	v_mfma_f32_16x16x32_bf16 v[104:107], v[200:203], v[172:175], v[104:107]
	v_add_f32_e32 v207, v205, v196
	v_exp_f32_e32 v206, v199
	v_mfma_f32_16x16x32_bf16 v[40:43], v[200:203], v[176:179], v[40:43]
	ds_read_b64_tr_b16 v[196:197], v238 offset:51200
	ds_read_b64_tr_b16 v[198:199], v238 offset:59392
	s_waitcnt lgkmcnt(4)
	v_mfma_f32_16x16x32_bf16 v[36:39], v[180:183], v[176:179], v[36:39]
	v_add_f32_e32 v200, v206, v207
	v_exp_f32_e32 v192, v192
	v_mfma_f32_16x16x32_bf16 v[100:103], v[180:183], v[172:175], v[100:103]
	ds_read_b64_tr_b16 v[180:181], v241 offset:51200
	ds_read_b64_tr_b16 v[182:183], v241 offset:59392
	s_waitcnt lgkmcnt(4)
	v_mfma_f32_16x16x32_bf16 v[96:99], v[184:187], v[172:175], v[96:99]
	v_add_f32_e32 v201, v192, v226
	v_exp_f32_e32 v193, v193
	v_mfma_f32_16x16x32_bf16 v[32:35], v[184:187], v[176:179], v[32:35]
	ds_read_b64_tr_b16 v[184:185], v0 offset:52224
	ds_read_b64_tr_b16 v[186:187], v0 offset:60416
	s_waitcnt lgkmcnt(4)
	v_mfma_f32_16x16x32_bf16 v[28:31], v[196:199], v[176:179], v[28:31]
	v_exp_f32_e32 v0, v194
	v_add_f32_e32 v194, v193, v201
	v_mfma_f32_16x16x32_bf16 v[92:95], v[196:199], v[172:175], v[92:95]
	ds_read_b64_tr_b16 v[196:197], v229 offset:52224
	ds_read_b64_tr_b16 v[198:199], v229 offset:60416
	s_waitcnt lgkmcnt(4)
	v_mfma_f32_16x16x32_bf16 v[88:91], v[180:183], v[172:175], v[88:91]
	v_add_f32_e32 v194, v0, v194
	v_exp_f32_e32 v195, v195
	v_mfma_f32_16x16x32_bf16 v[24:27], v[180:183], v[176:179], v[24:27]
	ds_read_b64_tr_b16 v[180:181], v238 offset:52224
	ds_read_b64_tr_b16 v[182:183], v238 offset:60416
	s_waitcnt lgkmcnt(4)
	v_mfma_f32_16x16x32_bf16 v[20:23], v[184:187], v[176:179], v[20:23]
	v_exp_f32_e32 v201, v188
	v_add_f32_e32 v188, v195, v194
	v_mfma_f32_16x16x32_bf16 v[84:87], v[184:187], v[172:175], v[84:87]
	ds_read_b64_tr_b16 v[184:185], v241 offset:52224
	ds_read_b64_tr_b16 v[186:187], v241 offset:60416
	s_waitcnt lgkmcnt(4)
	v_mfma_f32_16x16x32_bf16 v[80:83], v[196:199], v[172:175], v[80:83]
	v_exp_f32_e32 v194, v189
	v_add_f32_e32 v189, v201, v200
	v_mfma_f32_16x16x32_bf16 v[16:19], v[196:199], v[176:179], v[16:19]
	s_waitcnt lgkmcnt(2)
	v_mfma_f32_16x16x32_bf16 v[12:15], v[180:183], v[176:179], v[12:15]
	v_add_f32_e32 v189, v194, v189
	v_exp_f32_e32 v190, v190
	v_mfma_f32_16x16x32_bf16 v[76:79], v[180:183], v[172:175], v[76:79]
	s_waitcnt lgkmcnt(0)
	v_mfma_f32_16x16x32_bf16 v[8:11], v[184:187], v[176:179], v[8:11]
	v_add_f32_e32 v176, v190, v189
	v_exp_f32_e32 v191, v191
	v_mfma_f32_16x16x32_bf16 v[72:75], v[184:187], v[172:175], v[72:75]
	s_cmp_lt_u32 s20, s73
	v_add_f32_e32 v172, v191, v176
	s_cselect_b64 vcc, -1, 0
	v_cndmask_b32_e32 v189, 0, v188, vcc
	v_cndmask_b32_e32 v188, 0, v172, vcc
	v_cvt_pk_bf16_f32 v184, v2, v3
	v_cvt_pk_bf16_f32 v185, v242, v243
	v_cvt_pk_bf16_f32 v186, v248, v249
	v_cvt_pk_bf16_f32 v187, v239, v250
	v_cvt_pk_bf16_f32 v180, v244, v245
	v_cvt_pk_bf16_f32 v181, v246, v247
	v_cvt_pk_bf16_f32 v182, v234, v235
	v_cvt_pk_bf16_f32 v183, v236, v237
	v_cvt_pk_bf16_f32 v176, v220, v222
	v_cvt_pk_bf16_f32 v177, v223, v224
	v_cvt_pk_bf16_f32 v178, v192, v193
	v_cvt_pk_bf16_f32 v179, v0, v195
	v_cvt_pk_bf16_f32 v172, v225, v204
	v_cvt_pk_bf16_f32 v173, v205, v206
	v_cvt_pk_bf16_f32 v174, v201, v194
	v_cvt_pk_bf16_f32 v175, v190, v191
	v_pk_add_f32 v[208:209], v[208:209], v[188:189]
